# phase 1: the 16-gate cross-lane reduce-scatter uses DPP adds (row_mirror / row_half_mirror with bank masks, quad_perm) instead of ds_bpermute round trips and selects
# speedup vs baseline: 1.0077x; 1.0070x over previous
; #define LAS __attribute__((address_space(3)))
; __device__ __forceinline__ unsigned cvt_pk_bf16(float lo, float hi) { unsigned r; asm volatile("v_cvt_pk_bf16_f32 %0, %1, %2" : "=v"(r) : "v"(lo), "v"(hi)); return r; }
; __device__ __forceinline__ float dot4(const f32x4 a, const f32x4 b) { return (a[0] * b[0] + a[1] * b[1]) + (a[2] * b[2] + a[3] * b[3]); }
; __device__ __forceinline__ void norm_rows2(const f32x4 (&xa)[4], const f32x4 (&xb)[4], const LAS float* gsa, const LAS float* sha, const LAS float* gsb, const LAS float* shb, const LAS float* WgT, ...
;     float ssa = 0.f, ssb = 0.f;
; #pragma unroll
;     for (int i = 0; i < 4; ++i) { ssa += dot4(xa[i], xa[i]); ssb += dot4(xb[i], xb[i]); }
;     ssa = wave_sum(ssa); ssb = wave_sum(ssb);
;     const float ra = rsqrtf(ssa * (1.0f / 1024.0f) + 1e-6f), rb = rsqrtf(ssb * (1.0f / 1024.0f) + 1e-6f);
;     f32x4 ya[4], yb[4];
; #pragma unroll
;     for (int i = 0; i < 4; ++i) {
;         ya[i] = xa[i] * ra * *(const LAS f32x4*)(gsa + i * 256 + lane * 4) + *(const LAS f32x4*)(sha + i * 256 + lane * 4);
;         yb[i] = xb[i] * rb * *(const LAS f32x4*)(gsb + i * 256 + lane * 4) + *(const LAS f32x4*)(shb + i * 256 + lane * 4);
;         u32x2 w; w.x = cvt_pk_bf16(ya[i][0], ya[i][1]); w.y = cvt_pk_bf16(ya[i][2], ya[i][3]); *(u32x2*)(oa + i * 256 + lane * 4) = w;
;         u32x2 v; v.x = cvt_pk_bf16(yb[i][0], yb[i][1]); v.y = cvt_pk_bf16(yb[i][2], yb[i][3]); *(u32x2*)(ob + i * 256 + lane * 4) = v; }
; __device__ void phase1(const Params& p, LAS unsigned char* lds) {
;     ...
;             const int ra_ = pr < 4 ? rbase + 2 * pr : rbase + 7;
;             const float* xa_ = p.x + (size_t)ra_ * 1024; const float* xb_ = pr < 4 ? xa_ + 1024 : p.ctx + (size_t)crow * 1024;
;             f32x4 xa[4], xb[4];
; #pragma unroll
;             for (int i = 0; i < 4; ++i) { xa[i] = __builtin_nontemporal_load((const f32x4*)(xa_ + i * 256 + lane * 4)); xb[i] = __builtin_nontemporal_load((const f32x4*)(xb_ + i * 256 + lane * 4)); }
;             const LAS float* gsb_ = pr < 4 ? gs : gsc; const LAS float* shb_ = pr < 4 ? sh : shc;
;             bf16_t* ob_ = pr < 4 ? AB + (size_t)(ra_ + 1) * 1024 : AB + (size_t)(16384 + crow) * 1024;
;             float* gb_ = pr < 4 ? gl + ((ra_ + 1) & 2047) : gc;
;             norm_rows2(xa, xb, gs, sh, gsb_, shb_, WgT, AB + (size_t)ra_ * 1024, ob_, gl + (ra_ & 2047), gb_, p.gate_b, lane);
.LBB0_110:
	s_add_i32 s28, 0, 0x2000
	s_add_i32 s29, 0, 0x3000
	s_add_i32 s30, 0, 0x1000
	s_cmp_eq_u32 s82, 8
	v_add_u32_e32 v0, s82, v105
	s_cselect_b64 vcc, -1, 0
	v_cndmask_b32_e32 v60, v0, v108, vcc
	v_ashrrev_i32_e32 v61, 31, v60
	v_lshlrev_b64 v[0:1], 12, v[60:61]
	v_lshl_add_u64 v[0:1], s[36:37], 0, v[0:1]
	v_mov_b32_e32 v49, v35
	s_waitcnt lgkmcnt(0)
	v_lshl_add_u64 v[2:3], v[0:1], 0, v[48:49]
	s_mov_b64 s[38:39], 0x1000
	global_load_dwordx4 v[24:27], v[2:3], off nt
	global_load_dwordx4 v[20:23], v[2:3], off offset:1024 nt
	global_load_dwordx4 v[4:7], v[2:3], off offset:3072 nt
	global_load_dwordx4 v[12:15], v[2:3], off offset:2048 nt
	v_lshl_add_u64 v[0:1], v[0:1], 0, s[38:39]
	v_cndmask_b32_e32 v1, v1, v59, vcc
	v_cndmask_b32_e32 v0, v0, v58, vcc
	v_lshl_add_u64 v[8:9], v[0:1], 0, v[48:49]
	global_load_dwordx4 v[28:31], v[8:9], off nt
	global_load_dwordx4 v[16:19], v[8:9], off offset:1024 nt
	global_load_dwordx4 v[0:3], v[8:9], off offset:3072 nt
	s_nop 0
	global_load_dwordx4 v[8:11], v[8:9], off offset:2048 nt
	s_and_b64 s[38:39], vcc, exec
	s_cselect_b32 s28, s28, 0
	s_cselect_b32 s29, s29, s30
	s_waitcnt vmcnt(7)
	v_pk_mul_f32 v[62:63], v[26:27], v[26:27]
	v_pk_mul_f32 v[64:65], v[24:25], v[24:25]
	s_waitcnt vmcnt(6)
	v_pk_mul_f32 v[66:67], v[22:23], v[22:23]
	v_pk_mul_f32 v[68:69], v[20:21], v[20:21]
	s_waitcnt vmcnt(4)
	v_mul_f32_e32 v70, v15, v15
	v_pk_mov_b32 v[72:73], v[64:65], v[62:63] op_sel:[1,0]
	v_mov_b32_e32 v65, v63
	v_pk_mov_b32 v[62:63], v[68:69], v[66:67] op_sel:[1,0]
	v_mov_b32_e32 v69, v67
	v_mul_f32_e32 v80, v7, v7
	v_mul_f32_e32 v34, v13, v13
	v_pk_fma_f32 v[70:71], v[14:15], v[14:15], v[70:71] op_sel_hi:[1,1,0]
	v_pk_add_f32 v[64:65], v[72:73], v[64:65]
	s_waitcnt vmcnt(3)
	v_pk_mul_f32 v[72:73], v[30:31], v[30:31]
	v_pk_mul_f32 v[74:75], v[28:29], v[28:29]
	v_pk_add_f32 v[62:63], v[62:63], v[68:69]
	s_waitcnt vmcnt(2)
	v_pk_mul_f32 v[68:69], v[18:19], v[18:19]
	v_pk_mul_f32 v[76:77], v[16:17], v[16:17]
	v_mul_f32_e32 v49, v4, v4
	v_mul_f32_e32 v79, v5, v5
	v_mul_f32_e32 v78, v6, v6
	v_pk_fma_f32 v[66:67], v[12:13], v[12:13], v[34:35] op_sel_hi:[1,1,0]
	v_mov_b32_e32 v71, v80
	v_pk_mov_b32 v[80:81], v[74:75], v[72:73] op_sel:[1,0]
	v_mov_b32_e32 v75, v73
	v_pk_mov_b32 v[72:73], v[76:77], v[68:69] op_sel:[1,0]
	v_mov_b32_e32 v77, v69
	v_pk_add_f32 v[64:65], v[64:65], v[64:65] op_sel:[0,1] op_sel_hi:[1,0]
	v_pk_add_f32 v[62:63], v[62:63], v[62:63] op_sel:[0,1] op_sel_hi:[1,0]
	v_mov_b32_e32 v67, v78
	s_waitcnt vmcnt(0)
	v_mul_f32_e32 v34, v9, v9
	v_mul_f32_e32 v78, v11, v11
	v_pk_add_f32 v[74:75], v[80:81], v[74:75]
	v_pk_add_f32 v[72:73], v[72:73], v[76:77]
	v_mov_b32_e32 v65, v49
	v_mov_b32_e32 v63, v79
	v_mul_f32_e32 v82, v0, v0
	v_mul_f32_e32 v83, v1, v1
	v_mul_f32_e32 v84, v2, v2
	v_mul_f32_e32 v85, v3, v3
	v_pk_add_f32 v[66:67], v[66:67], v[70:71]
	v_pk_fma_f32 v[68:69], v[8:9], v[8:9], v[34:35] op_sel_hi:[1,1,0]
	v_pk_fma_f32 v[70:71], v[10:11], v[10:11], v[78:79] op_sel_hi:[1,1,0]
	v_pk_add_f32 v[62:63], v[64:65], v[62:63]
	v_pk_add_f32 v[64:65], v[74:75], v[74:75] op_sel:[0,1] op_sel_hi:[1,0]
	v_pk_add_f32 v[72:73], v[72:73], v[72:73] op_sel:[0,1] op_sel_hi:[1,0]
	v_mov_b32_e32 v69, v84
	v_mov_b32_e32 v71, v85
	v_mov_b32_e32 v65, v82
	v_mov_b32_e32 v73, v83
	v_pk_add_f32 v[68:69], v[68:69], v[70:71]
	v_pk_add_f32 v[64:65], v[64:65], v[72:73]
	v_pk_add_f32 v[62:63], v[62:63], v[66:67]
	v_pk_add_f32 v[64:65], v[64:65], v[68:69]
	v_mov_b32_e32 v67, v62
	v_mov_b32_e32 v66, v64
	v_mov_b32_e32 v62, v65
	v_pk_add_f32 v[62:63], v[66:67], v[62:63]
	ds_bpermute_b32 v65, v53, v63
	ds_bpermute_b32 v64, v53, v62
	v_lshlrev_b64 v[76:77], 11, v[60:61]
	v_add_u32_e32 v49, s28, v48
	v_add_u32_e32 v61, s29, v48
	v_add_u32_e32 v34, 1, v60
	s_waitcnt lgkmcnt(0)
	v_pk_add_f32 v[62:63], v[62:63], v[64:65]
	ds_bpermute_b32 v65, v94, v63
	ds_bpermute_b32 v64, v94, v62
	v_cndmask_b32_e32 v74, v34, v109, vcc
	v_ashrrev_i32_e32 v75, 31, v74
	v_lshlrev_b64 v[74:75], 11, v[74:75]
	v_lshl_add_u64 v[78:79], v[36:37], 0, v[76:77]
	s_waitcnt lgkmcnt(0)
	v_pk_add_f32 v[62:63], v[62:63], v[64:65]
	ds_bpermute_b32 v73, v95, v63
	ds_bpermute_b32 v72, v95, v62
	ds_read_b128 v[64:67], v99
	ds_read_b128 v[68:71], v99 offset:4096
	ds_read_b128 v[80:83], v49
	ds_read_b128 v[84:87], v61
	s_waitcnt lgkmcnt(4)
	v_pk_add_f32 v[62:63], v[62:63], v[72:73]
	ds_bpermute_b32 v73, v96, v63
	ds_bpermute_b32 v72, v96, v62
	s_waitcnt lgkmcnt(0)
	v_pk_add_f32 v[62:63], v[62:63], v[72:73]
	ds_bpermute_b32 v73, v97, v63
	ds_bpermute_b32 v72, v97, v62
	s_waitcnt lgkmcnt(0)
	v_pk_add_f32 v[62:63], v[62:63], v[72:73]
	ds_bpermute_b32 v73, v98, v63
	ds_bpermute_b32 v72, v98, v62
	s_waitcnt lgkmcnt(0)
	v_pk_add_f32 v[62:63], v[62:63], v[72:73]
	s_nop 0
	v_pk_fma_f32 v[62:63], v[62:63], s[46:47], v[50:51] op_sel_hi:[1,0,0]
	s_nop 0
	v_mul_f32_e32 v72, 0x4b800000, v63
	v_cmp_gt_f32_e64 s[28:29], s34, v63
	v_mul_f32_e32 v73, 0x4b800000, v62
	v_cmp_gt_f32_e64 s[30:31], s34, v62
	v_cndmask_b32_e64 v63, v63, v72, s[28:29]
	v_rsq_f32_e32 v72, v63
	v_cndmask_b32_e64 v62, v62, v73, s[30:31]
	v_rsq_f32_e32 v73, v62
	v_lshl_add_u64 v[62:63], v[36:37], 0, v[74:75]
	v_mul_f32_e32 v74, 0x45800000, v72
	v_cndmask_b32_e64 v88, v72, v74, s[28:29]
	v_mul_f32_e32 v75, 0x45800000, v73
	v_cndmask_b32_e64 v90, v73, v75, s[30:31]
	v_pk_mul_f32 v[24:25], v[24:25], v[88:89] op_sel_hi:[1,0]
	v_pk_mul_f32 v[26:27], v[26:27], v[88:89] op_sel_hi:[1,0]
	v_pk_mul_f32 v[28:29], v[28:29], v[90:91] op_sel_hi:[1,0]
	v_pk_mul_f32 v[30:31], v[30:31], v[90:91] op_sel_hi:[1,0]
	v_pk_mul_f32 v[92:93], v[20:21], v[88:89] op_sel_hi:[1,0]
	v_pk_fma_f32 v[74:75], v[66:67], v[26:27], v[70:71]
	v_pk_fma_f32 v[76:77], v[64:65], v[24:25], v[68:69]
	v_pk_mul_f32 v[110:111], v[22:23], v[88:89] op_sel_hi:[1,0]
	v_cvt_pk_bf16_f32 v20, v76, v77
	v_cvt_pk_bf16_f32 v21, v74, v75
	v_pk_fma_f32 v[70:71], v[82:83], v[30:31], v[86:87]
	v_pk_fma_f32 v[72:73], v[80:81], v[28:29], v[84:85]
	global_store_dwordx2 v[78:79], v[20:21], off
	v_cvt_pk_bf16_f32 v64, v72, v73
	v_cvt_pk_bf16_f32 v65, v70, v71
	ds_read_b128 v[20:23], v99 offset:1024
	ds_read_b128 v[24:27], v99 offset:5120
	ds_read_b128 v[28:31], v49 offset:1024
	ds_read_b128 v[80:83], v61 offset:1024
	v_pk_mul_f32 v[16:17], v[16:17], v[90:91] op_sel_hi:[1,0]
	global_store_dwordx2 v[62:63], v[64:65], off
	v_pk_mul_f32 v[18:19], v[18:19], v[90:91] op_sel_hi:[1,0]
	s_waitcnt lgkmcnt(2)
; #define LAS __attribute__((address_space(3)))
; __device__ __forceinline__ unsigned cvt_pk_bf16(float lo, float hi) { unsigned r; asm volatile("v_cvt_pk_bf16_f32 %0, %1, %2" : "=v"(r) : "v"(lo), "v"(hi)); return r; }
; __device__ __forceinline__ float dot4(const f32x4 a, const f32x4 b) { return (a[0] * b[0] + a[1] * b[1]) + (a[2] * b[2] + a[3] * b[3]); }
; __device__ __forceinline__ void norm_rows2(const f32x4 (&xa)[4], const f32x4 (&xb)[4], const LAS float* gsa, const LAS float* sha, const LAS float* gsb, const LAS float* shb, const LAS float* WgT, ...
;     ...
;         ya[i] = xa[i] * ra * *(const LAS f32x4*)(gsa + i * 256 + lane * 4) + *(const LAS f32x4*)(sha + i * 256 + lane * 4);
;         yb[i] = xb[i] * rb * *(const LAS f32x4*)(gsb + i * 256 + lane * 4) + *(const LAS f32x4*)(shb + i * 256 + lane * 4);
;         u32x2 w; w.x = cvt_pk_bf16(ya[i][0], ya[i][1]); w.y = cvt_pk_bf16(ya[i][2], ya[i][3]); *(u32x2*)(oa + i * 256 + lane * 4) = w;
;         u32x2 v; v.x = cvt_pk_bf16(yb[i][0], yb[i][1]); v.y = cvt_pk_bf16(yb[i][2], yb[i][3]); *(u32x2*)(ob + i * 256 + lane * 4) = v; }
;     f32x4 pa[4], pb[4];
; #pragma unroll
;     for (int jq = 0; jq < 4; ++jq) { f32x4 sa = (f32x4){0.f, 0.f, 0.f, 0.f}, sb = sa;
; #pragma unroll
;         for (int i = 0; i < 4; ++i) { const LAS float* wp = WgT + (jq * 4) * 1024 + i * 256 + lane * 4;
;             const f32x4 w0 = *(const LAS f32x4*)wp, w1 = *(const LAS f32x4*)(wp + 1024), w2 = *(const LAS f32x4*)(wp + 2048), w3 = *(const LAS f32x4*)(wp + 3072);
;             sa += (f32x4){dot4(ya[i], w0), dot4(ya[i], w1), dot4(ya[i], w2), dot4(ya[i], w3)};
;             sb += (f32x4){dot4(yb[i], w0), dot4(yb[i], w1), dot4(yb[i], w2), dot4(yb[i], w3)}; }
	v_pk_fma_f32 v[66:67], v[110:111], v[22:23], v[26:27]
	v_pk_fma_f32 v[68:69], v[92:93], v[20:21], v[24:25]
	s_waitcnt lgkmcnt(0)
	v_pk_fma_f32 v[64:65], v[16:17], v[28:29], v[80:81]
	v_cvt_pk_bf16_f32 v16, v68, v69
	v_cvt_pk_bf16_f32 v17, v66, v67
	v_pk_fma_f32 v[30:31], v[18:19], v[30:31], v[82:83]
	global_store_dwordx2 v[78:79], v[16:17], off offset:512
	v_cvt_pk_bf16_f32 v16, v64, v65
	v_cvt_pk_bf16_f32 v17, v30, v31
	global_store_dwordx2 v[62:63], v[16:17], off offset:512
	ds_read_b128 v[16:19], v99 offset:2048
	ds_read_b128 v[20:23], v99 offset:6144
	ds_read_b128 v[24:27], v49 offset:2048
	ds_read_b128 v[80:83], v61 offset:2048
	v_pk_mul_f32 v[12:13], v[12:13], v[88:89] op_sel_hi:[1,0]
	v_pk_mul_f32 v[14:15], v[14:15], v[88:89] op_sel_hi:[1,0]
	v_pk_mul_f32 v[8:9], v[8:9], v[90:91] op_sel_hi:[1,0]
	s_waitcnt lgkmcnt(2)
	v_pk_fma_f32 v[14:15], v[14:15], v[18:19], v[22:23]
	v_pk_fma_f32 v[18:19], v[12:13], v[16:17], v[20:21]
	v_pk_mul_f32 v[10:11], v[10:11], v[90:91] op_sel_hi:[1,0]
	s_waitcnt lgkmcnt(0)
	v_pk_fma_f32 v[20:21], v[8:9], v[24:25], v[80:81]
	v_cvt_pk_bf16_f32 v8, v18, v19
	v_cvt_pk_bf16_f32 v9, v14, v15
	v_pk_fma_f32 v[16:17], v[10:11], v[26:27], v[82:83]
	global_store_dwordx2 v[78:79], v[8:9], off offset:1024
	v_cvt_pk_bf16_f32 v8, v20, v21
	v_cvt_pk_bf16_f32 v9, v16, v17
	global_store_dwordx2 v[62:63], v[8:9], off offset:1024
	ds_read_b128 v[8:11], v99 offset:3072
	ds_read_b128 v[22:25], v99 offset:7168
	v_pk_mul_f32 v[12:13], v[4:5], v[88:89] op_sel_hi:[1,0]
	v_pk_mul_f32 v[80:81], v[6:7], v[88:89] op_sel_hi:[1,0]
	ds_read_b128 v[4:7], v49 offset:3072
	ds_read_b128 v[26:29], v61 offset:3072
	v_pk_mul_f32 v[0:1], v[0:1], v[90:91] op_sel_hi:[1,0]
	s_waitcnt lgkmcnt(2)
	v_pk_fma_f32 v[10:11], v[80:81], v[10:11], v[24:25]
	v_pk_fma_f32 v[12:13], v[12:13], v[8:9], v[22:23]
	v_pk_mul_f32 v[2:3], v[2:3], v[90:91] op_sel_hi:[1,0]
	s_waitcnt lgkmcnt(0)
	v_pk_fma_f32 v[8:9], v[0:1], v[4:5], v[26:27]
	v_cvt_pk_bf16_f32 v0, v12, v13
	v_cvt_pk_bf16_f32 v1, v10, v11
	v_pk_fma_f32 v[6:7], v[2:3], v[6:7], v[28:29]
	global_store_dwordx2 v[78:79], v[0:1], off offset:1536
	v_cvt_pk_bf16_f32 v4, v8, v9
	v_cvt_pk_bf16_f32 v5, v6, v7
	global_store_dwordx2 v[62:63], v[4:5], off offset:1536
	ds_read_b128 v[110:113], v99 offset:16384
	ds_read_b128 v[114:117], v99 offset:20480
	ds_read_b128 v[118:121], v99 offset:24576
	ds_read_b128 v[122:125], v99 offset:28672
	ds_read_b128 v[126:129], v99 offset:32768
	ds_read_b128 v[130:133], v99 offset:36864
	ds_read_b128 v[134:137], v99 offset:40960
	ds_read_b128 v[138:141], v99 offset:45056
	ds_read_b128 v[142:145], v99 offset:49152
	ds_read_b128 v[146:149], v99 offset:53248
	ds_read_b128 v[150:153], v99 offset:57344
	ds_read_b128 v[154:157], v99 offset:61440
	s_waitcnt lgkmcnt(8)
	v_pk_mul_f32 v[160:161], v[72:73], v[110:111]
	v_pk_mul_f32 v[192:193], v[76:77], v[110:111]
	v_pk_mul_f32 v[162:163], v[72:73], v[114:115]
	v_pk_mul_f32 v[194:195], v[76:77], v[114:115]
	v_pk_mul_f32 v[164:165], v[72:73], v[118:119]
	v_pk_mul_f32 v[196:197], v[76:77], v[118:119]
	v_pk_mul_f32 v[166:167], v[72:73], v[122:123]
	v_pk_mul_f32 v[198:199], v[76:77], v[122:123]
	v_pk_fma_f32 v[160:161], v[70:71], v[112:113], v[160:161]
	v_pk_fma_f32 v[192:193], v[74:75], v[112:113], v[192:193]
	v_pk_fma_f32 v[162:163], v[70:71], v[116:117], v[162:163]
	v_pk_fma_f32 v[194:195], v[74:75], v[116:117], v[194:195]
	v_pk_fma_f32 v[164:165], v[70:71], v[120:121], v[164:165]
	v_pk_fma_f32 v[196:197], v[74:75], v[120:121], v[196:197]
	v_pk_fma_f32 v[166:167], v[70:71], v[124:125], v[166:167]
	v_pk_fma_f32 v[198:199], v[74:75], v[124:125], v[198:199]
	ds_read_b128 v[228:231], v100 offset:49152
	ds_read_b128 v[232:235], v100 offset:53248
	ds_read_b128 v[236:239], v100 offset:57344
	ds_read_b128 v[240:243], v100 offset:61440
	s_waitcnt lgkmcnt(8)
	v_pk_mul_f32 v[168:169], v[72:73], v[126:127]
	v_pk_mul_f32 v[200:201], v[76:77], v[126:127]
	v_pk_mul_f32 v[170:171], v[72:73], v[130:131]
	v_pk_mul_f32 v[202:203], v[76:77], v[130:131]
	v_pk_mul_f32 v[172:173], v[72:73], v[134:135]
	v_pk_mul_f32 v[204:205], v[76:77], v[134:135]
	v_pk_mul_f32 v[174:175], v[72:73], v[138:139]
	v_pk_mul_f32 v[206:207], v[76:77], v[138:139]
	v_pk_fma_f32 v[168:169], v[70:71], v[128:129], v[168:169]
	v_pk_fma_f32 v[200:201], v[74:75], v[128:129], v[200:201]
	v_pk_fma_f32 v[170:171], v[70:71], v[132:133], v[170:171]
	v_pk_fma_f32 v[202:203], v[74:75], v[132:133], v[202:203]
	v_pk_fma_f32 v[172:173], v[70:71], v[136:137], v[172:173]
	v_pk_fma_f32 v[204:205], v[74:75], v[136:137], v[204:205]
	v_pk_fma_f32 v[174:175], v[70:71], v[140:141], v[174:175]
	v_pk_fma_f32 v[206:207], v[74:75], v[140:141], v[206:207]
	ds_read_b128 v[110:113], v99 offset:17408
	ds_read_b128 v[114:117], v99 offset:21504
	ds_read_b128 v[118:121], v99 offset:25600
	ds_read_b128 v[122:125], v99 offset:29696
	s_waitcnt lgkmcnt(8)
	v_pk_mul_f32 v[176:177], v[72:73], v[142:143]
	v_pk_mul_f32 v[208:209], v[76:77], v[142:143]
	v_pk_mul_f32 v[178:179], v[72:73], v[146:147]
	v_pk_mul_f32 v[210:211], v[76:77], v[146:147]
	v_pk_mul_f32 v[180:181], v[72:73], v[150:151]
	v_pk_mul_f32 v[212:213], v[76:77], v[150:151]
	v_pk_mul_f32 v[182:183], v[72:73], v[154:155]
	v_pk_mul_f32 v[214:215], v[76:77], v[154:155]
	v_pk_fma_f32 v[176:177], v[70:71], v[144:145], v[176:177]
	v_pk_fma_f32 v[208:209], v[74:75], v[144:145], v[208:209]
	v_pk_fma_f32 v[178:179], v[70:71], v[148:149], v[178:179]
	v_pk_fma_f32 v[210:211], v[74:75], v[148:149], v[210:211]
	v_pk_fma_f32 v[180:181], v[70:71], v[152:153], v[180:181]
	v_pk_fma_f32 v[212:213], v[74:75], v[152:153], v[212:213]
	v_pk_fma_f32 v[182:183], v[70:71], v[156:157], v[182:183]
	v_pk_fma_f32 v[214:215], v[74:75], v[156:157], v[214:215]
	ds_read_b128 v[126:129], v99 offset:33792
	ds_read_b128 v[130:133], v99 offset:37888
	ds_read_b128 v[134:137], v99 offset:41984
	ds_read_b128 v[138:141], v99 offset:46080
	s_waitcnt lgkmcnt(8)
; #define LAS __attribute__((address_space(3)))
; __device__ __forceinline__ float dot4(const f32x4 a, const f32x4 b) { return (a[0] * b[0] + a[1] * b[1]) + (a[2] * b[2] + a[3] * b[3]); }
; __device__ __forceinline__ void norm_rows2(const f32x4 (&xa)[4], const f32x4 (&xb)[4], const LAS float* gsa, const LAS float* sha, const LAS float* gsb, const LAS float* shb, const LAS float* WgT, ...
;     ...
;     for (int jq = 0; jq < 4; ++jq) { f32x4 sa = (f32x4){0.f, 0.f, 0.f, 0.f}, sb = sa;
; #pragma unroll
;         for (int i = 0; i < 4; ++i) { const LAS float* wp = WgT + (jq * 4) * 1024 + i * 256 + lane * 4;
;             const f32x4 w0 = *(const LAS f32x4*)wp, w1 = *(const LAS f32x4*)(wp + 1024), w2 = *(const LAS f32x4*)(wp + 2048), w3 = *(const LAS f32x4*)(wp + 3072);
;             sa += (f32x4){dot4(ya[i], w0), dot4(ya[i], w1), dot4(ya[i], w2), dot4(ya[i], w3)};
;             sb += (f32x4){dot4(yb[i], w0), dot4(yb[i], w1), dot4(yb[i], w2), dot4(yb[i], w3)}; }
	v_pk_mul_f32 v[184:185], v[72:73], v[228:229]
	v_pk_mul_f32 v[216:217], v[76:77], v[228:229]
	v_pk_mul_f32 v[186:187], v[72:73], v[232:233]
	v_pk_mul_f32 v[218:219], v[76:77], v[232:233]
	v_pk_mul_f32 v[188:189], v[72:73], v[236:237]
	v_pk_mul_f32 v[220:221], v[76:77], v[236:237]
	v_pk_mul_f32 v[190:191], v[72:73], v[240:241]
	v_pk_mul_f32 v[222:223], v[76:77], v[240:241]
	v_pk_fma_f32 v[184:185], v[70:71], v[230:231], v[184:185]
	v_pk_fma_f32 v[216:217], v[74:75], v[230:231], v[216:217]
	v_pk_fma_f32 v[186:187], v[70:71], v[234:235], v[186:187]
	v_pk_fma_f32 v[218:219], v[74:75], v[234:235], v[218:219]
	v_pk_fma_f32 v[188:189], v[70:71], v[238:239], v[188:189]
	v_pk_fma_f32 v[220:221], v[74:75], v[238:239], v[220:221]
	v_pk_fma_f32 v[190:191], v[70:71], v[242:243], v[190:191]
	v_pk_fma_f32 v[222:223], v[74:75], v[242:243], v[222:223]
	ds_read_b128 v[142:145], v99 offset:50176
	ds_read_b128 v[146:149], v99 offset:54272
	ds_read_b128 v[150:153], v99 offset:58368
	ds_read_b128 v[154:157], v99 offset:62464
	s_waitcnt lgkmcnt(8)
	v_pk_fma_f32 v[160:161], v[64:65], v[110:111], v[160:161]
	v_pk_fma_f32 v[192:193], v[68:69], v[110:111], v[192:193]
	v_pk_fma_f32 v[162:163], v[64:65], v[114:115], v[162:163]
	v_pk_fma_f32 v[194:195], v[68:69], v[114:115], v[194:195]
	v_pk_fma_f32 v[164:165], v[64:65], v[118:119], v[164:165]
	v_pk_fma_f32 v[196:197], v[68:69], v[118:119], v[196:197]
	v_pk_fma_f32 v[166:167], v[64:65], v[122:123], v[166:167]
	v_pk_fma_f32 v[198:199], v[68:69], v[122:123], v[198:199]
	v_pk_fma_f32 v[160:161], v[30:31], v[112:113], v[160:161]
	v_pk_fma_f32 v[192:193], v[66:67], v[112:113], v[192:193]
	v_pk_fma_f32 v[162:163], v[30:31], v[116:117], v[162:163]
	v_pk_fma_f32 v[194:195], v[66:67], v[116:117], v[194:195]
	v_pk_fma_f32 v[164:165], v[30:31], v[120:121], v[164:165]
	v_pk_fma_f32 v[196:197], v[66:67], v[120:121], v[196:197]
	v_pk_fma_f32 v[166:167], v[30:31], v[124:125], v[166:167]
	v_pk_fma_f32 v[198:199], v[66:67], v[124:125], v[198:199]
	ds_read_b128 v[228:231], v100 offset:50176
	ds_read_b128 v[232:235], v100 offset:54272
	ds_read_b128 v[236:239], v100 offset:58368
	ds_read_b128 v[240:243], v100 offset:62464
	s_waitcnt lgkmcnt(8)
	v_pk_fma_f32 v[168:169], v[64:65], v[126:127], v[168:169]
	v_pk_fma_f32 v[200:201], v[68:69], v[126:127], v[200:201]
	v_pk_fma_f32 v[170:171], v[64:65], v[130:131], v[170:171]
	v_pk_fma_f32 v[202:203], v[68:69], v[130:131], v[202:203]
	v_pk_fma_f32 v[172:173], v[64:65], v[134:135], v[172:173]
	v_pk_fma_f32 v[204:205], v[68:69], v[134:135], v[204:205]
	v_pk_fma_f32 v[174:175], v[64:65], v[138:139], v[174:175]
	v_pk_fma_f32 v[206:207], v[68:69], v[138:139], v[206:207]
	v_pk_fma_f32 v[168:169], v[30:31], v[128:129], v[168:169]
	v_pk_fma_f32 v[200:201], v[66:67], v[128:129], v[200:201]
	v_pk_fma_f32 v[170:171], v[30:31], v[132:133], v[170:171]
	v_pk_fma_f32 v[202:203], v[66:67], v[132:133], v[202:203]
	v_pk_fma_f32 v[172:173], v[30:31], v[136:137], v[172:173]
	v_pk_fma_f32 v[204:205], v[66:67], v[136:137], v[204:205]
	v_pk_fma_f32 v[174:175], v[30:31], v[140:141], v[174:175]
	v_pk_fma_f32 v[206:207], v[66:67], v[140:141], v[206:207]
	ds_read_b128 v[110:113], v99 offset:18432
	ds_read_b128 v[114:117], v99 offset:22528
	ds_read_b128 v[118:121], v99 offset:26624
	ds_read_b128 v[122:125], v99 offset:30720
	s_waitcnt lgkmcnt(8)
	v_pk_fma_f32 v[176:177], v[64:65], v[142:143], v[176:177]
	v_pk_fma_f32 v[208:209], v[68:69], v[142:143], v[208:209]
	v_pk_fma_f32 v[178:179], v[64:65], v[146:147], v[178:179]
	v_pk_fma_f32 v[210:211], v[68:69], v[146:147], v[210:211]
	v_pk_fma_f32 v[180:181], v[64:65], v[150:151], v[180:181]
	v_pk_fma_f32 v[212:213], v[68:69], v[150:151], v[212:213]
	v_pk_fma_f32 v[182:183], v[64:65], v[154:155], v[182:183]
	v_pk_fma_f32 v[214:215], v[68:69], v[154:155], v[214:215]
	v_pk_fma_f32 v[176:177], v[30:31], v[144:145], v[176:177]
	v_pk_fma_f32 v[208:209], v[66:67], v[144:145], v[208:209]
	v_pk_fma_f32 v[178:179], v[30:31], v[148:149], v[178:179]
	v_pk_fma_f32 v[210:211], v[66:67], v[148:149], v[210:211]
	v_pk_fma_f32 v[180:181], v[30:31], v[152:153], v[180:181]
	v_pk_fma_f32 v[212:213], v[66:67], v[152:153], v[212:213]
	v_pk_fma_f32 v[182:183], v[30:31], v[156:157], v[182:183]
	v_pk_fma_f32 v[214:215], v[66:67], v[156:157], v[214:215]
	ds_read_b128 v[126:129], v99 offset:34816
	ds_read_b128 v[130:133], v99 offset:38912
	ds_read_b128 v[134:137], v99 offset:43008
	ds_read_b128 v[138:141], v99 offset:47104
	s_waitcnt lgkmcnt(8)
	v_pk_fma_f32 v[184:185], v[64:65], v[228:229], v[184:185]
	v_pk_fma_f32 v[216:217], v[68:69], v[228:229], v[216:217]
	v_pk_fma_f32 v[186:187], v[64:65], v[232:233], v[186:187]
	v_pk_fma_f32 v[218:219], v[68:69], v[232:233], v[218:219]
	v_pk_fma_f32 v[188:189], v[64:65], v[236:237], v[188:189]
	v_pk_fma_f32 v[220:221], v[68:69], v[236:237], v[220:221]
	v_pk_fma_f32 v[190:191], v[64:65], v[240:241], v[190:191]
	v_pk_fma_f32 v[222:223], v[68:69], v[240:241], v[222:223]
	v_pk_fma_f32 v[184:185], v[30:31], v[230:231], v[184:185]
	v_pk_fma_f32 v[216:217], v[66:67], v[230:231], v[216:217]
	v_pk_fma_f32 v[186:187], v[30:31], v[234:235], v[186:187]
	v_pk_fma_f32 v[218:219], v[66:67], v[234:235], v[218:219]
	v_pk_fma_f32 v[188:189], v[30:31], v[238:239], v[188:189]
	v_pk_fma_f32 v[220:221], v[66:67], v[238:239], v[220:221]
	v_pk_fma_f32 v[190:191], v[30:31], v[242:243], v[190:191]
	v_pk_fma_f32 v[222:223], v[66:67], v[242:243], v[222:223]
	ds_read_b128 v[142:145], v99 offset:51200
	ds_read_b128 v[146:149], v99 offset:55296
	ds_read_b128 v[150:153], v99 offset:59392
	ds_read_b128 v[154:157], v99 offset:63488
	s_waitcnt lgkmcnt(8)
; #define LAS __attribute__((address_space(3)))
; __device__ __forceinline__ float dot4(const f32x4 a, const f32x4 b) { return (a[0] * b[0] + a[1] * b[1]) + (a[2] * b[2] + a[3] * b[3]); }
; __device__ __forceinline__ void norm_rows2(const f32x4 (&xa)[4], const f32x4 (&xb)[4], const LAS float* gsa, const LAS float* sha, const LAS float* gsb, const LAS float* shb, const LAS float* WgT, ...
;     ...
;     for (int jq = 0; jq < 4; ++jq) { f32x4 sa = (f32x4){0.f, 0.f, 0.f, 0.f}, sb = sa;
; #pragma unroll
;         for (int i = 0; i < 4; ++i) { const LAS float* wp = WgT + (jq * 4) * 1024 + i * 256 + lane * 4;
;             const f32x4 w0 = *(const LAS f32x4*)wp, w1 = *(const LAS f32x4*)(wp + 1024), w2 = *(const LAS f32x4*)(wp + 2048), w3 = *(const LAS f32x4*)(wp + 3072);
;             sa += (f32x4){dot4(ya[i], w0), dot4(ya[i], w1), dot4(ya[i], w2), dot4(ya[i], w3)};
;             sb += (f32x4){dot4(yb[i], w0), dot4(yb[i], w1), dot4(yb[i], w2), dot4(yb[i], w3)}; }
	v_pk_fma_f32 v[160:161], v[20:21], v[110:111], v[160:161]
	v_pk_fma_f32 v[192:193], v[18:19], v[110:111], v[192:193]
	v_pk_fma_f32 v[162:163], v[20:21], v[114:115], v[162:163]
	v_pk_fma_f32 v[194:195], v[18:19], v[114:115], v[194:195]
	v_pk_fma_f32 v[164:165], v[20:21], v[118:119], v[164:165]
	v_pk_fma_f32 v[196:197], v[18:19], v[118:119], v[196:197]
	v_pk_fma_f32 v[166:167], v[20:21], v[122:123], v[166:167]
	v_pk_fma_f32 v[198:199], v[18:19], v[122:123], v[198:199]
	v_pk_fma_f32 v[160:161], v[16:17], v[112:113], v[160:161]
	v_pk_fma_f32 v[192:193], v[14:15], v[112:113], v[192:193]
	v_pk_fma_f32 v[162:163], v[16:17], v[116:117], v[162:163]
	v_pk_fma_f32 v[194:195], v[14:15], v[116:117], v[194:195]
	v_pk_fma_f32 v[164:165], v[16:17], v[120:121], v[164:165]
	v_pk_fma_f32 v[196:197], v[14:15], v[120:121], v[196:197]
	v_pk_fma_f32 v[166:167], v[16:17], v[124:125], v[166:167]
	v_pk_fma_f32 v[198:199], v[14:15], v[124:125], v[198:199]
	ds_read_b128 v[228:231], v100 offset:51200
	ds_read_b128 v[232:235], v100 offset:55296
	ds_read_b128 v[236:239], v100 offset:59392
	ds_read_b128 v[240:243], v100 offset:63488
	s_waitcnt lgkmcnt(8)
	v_pk_fma_f32 v[168:169], v[20:21], v[126:127], v[168:169]
	v_pk_fma_f32 v[200:201], v[18:19], v[126:127], v[200:201]
	v_pk_fma_f32 v[170:171], v[20:21], v[130:131], v[170:171]
	v_pk_fma_f32 v[202:203], v[18:19], v[130:131], v[202:203]
	v_pk_fma_f32 v[172:173], v[20:21], v[134:135], v[172:173]
	v_pk_fma_f32 v[204:205], v[18:19], v[134:135], v[204:205]
	v_pk_fma_f32 v[174:175], v[20:21], v[138:139], v[174:175]
	v_pk_fma_f32 v[206:207], v[18:19], v[138:139], v[206:207]
	v_pk_fma_f32 v[168:169], v[16:17], v[128:129], v[168:169]
	v_pk_fma_f32 v[200:201], v[14:15], v[128:129], v[200:201]
	v_pk_fma_f32 v[170:171], v[16:17], v[132:133], v[170:171]
	v_pk_fma_f32 v[202:203], v[14:15], v[132:133], v[202:203]
	v_pk_fma_f32 v[172:173], v[16:17], v[136:137], v[172:173]
	v_pk_fma_f32 v[204:205], v[14:15], v[136:137], v[204:205]
	v_pk_fma_f32 v[174:175], v[16:17], v[140:141], v[174:175]
	v_pk_fma_f32 v[206:207], v[14:15], v[140:141], v[206:207]
	ds_read_b128 v[110:113], v99 offset:19456
	ds_read_b128 v[114:117], v99 offset:23552
	ds_read_b128 v[118:121], v99 offset:27648
	ds_read_b128 v[122:125], v99 offset:31744
	s_waitcnt lgkmcnt(8)
	v_pk_fma_f32 v[176:177], v[20:21], v[142:143], v[176:177]
	v_pk_fma_f32 v[208:209], v[18:19], v[142:143], v[208:209]
	v_pk_fma_f32 v[178:179], v[20:21], v[146:147], v[178:179]
	v_pk_fma_f32 v[210:211], v[18:19], v[146:147], v[210:211]
	v_pk_fma_f32 v[180:181], v[20:21], v[150:151], v[180:181]
	v_pk_fma_f32 v[212:213], v[18:19], v[150:151], v[212:213]
	v_pk_fma_f32 v[182:183], v[20:21], v[154:155], v[182:183]
	v_pk_fma_f32 v[214:215], v[18:19], v[154:155], v[214:215]
	v_pk_fma_f32 v[176:177], v[16:17], v[144:145], v[176:177]
	v_pk_fma_f32 v[208:209], v[14:15], v[144:145], v[208:209]
	v_pk_fma_f32 v[178:179], v[16:17], v[148:149], v[178:179]
	v_pk_fma_f32 v[210:211], v[14:15], v[148:149], v[210:211]
	v_pk_fma_f32 v[180:181], v[16:17], v[152:153], v[180:181]
	v_pk_fma_f32 v[212:213], v[14:15], v[152:153], v[212:213]
	v_pk_fma_f32 v[182:183], v[16:17], v[156:157], v[182:183]
	v_pk_fma_f32 v[214:215], v[14:15], v[156:157], v[214:215]
	ds_read_b128 v[126:129], v99 offset:35840
	ds_read_b128 v[130:133], v99 offset:39936
	ds_read_b128 v[134:137], v99 offset:44032
	ds_read_b128 v[138:141], v99 offset:48128
	s_waitcnt lgkmcnt(8)
	v_pk_fma_f32 v[184:185], v[20:21], v[228:229], v[184:185]
	v_pk_fma_f32 v[216:217], v[18:19], v[228:229], v[216:217]
	v_pk_fma_f32 v[186:187], v[20:21], v[232:233], v[186:187]
	v_pk_fma_f32 v[218:219], v[18:19], v[232:233], v[218:219]
	v_pk_fma_f32 v[188:189], v[20:21], v[236:237], v[188:189]
	v_pk_fma_f32 v[220:221], v[18:19], v[236:237], v[220:221]
	v_pk_fma_f32 v[190:191], v[20:21], v[240:241], v[190:191]
	v_pk_fma_f32 v[222:223], v[18:19], v[240:241], v[222:223]
	v_pk_fma_f32 v[184:185], v[16:17], v[230:231], v[184:185]
	v_pk_fma_f32 v[216:217], v[14:15], v[230:231], v[216:217]
	v_pk_fma_f32 v[186:187], v[16:17], v[234:235], v[186:187]
	v_pk_fma_f32 v[218:219], v[14:15], v[234:235], v[218:219]
	v_pk_fma_f32 v[188:189], v[16:17], v[238:239], v[188:189]
	v_pk_fma_f32 v[220:221], v[14:15], v[238:239], v[220:221]
	v_pk_fma_f32 v[190:191], v[16:17], v[242:243], v[190:191]
	v_pk_fma_f32 v[222:223], v[14:15], v[242:243], v[222:223]
	ds_read_b128 v[142:145], v99 offset:52224
	ds_read_b128 v[146:149], v99 offset:56320
	ds_read_b128 v[150:153], v99 offset:60416
	ds_read_b128 v[154:157], v99 offset:64512
	s_waitcnt lgkmcnt(8)
	v_pk_fma_f32 v[160:161], v[8:9], v[110:111], v[160:161]
	v_pk_fma_f32 v[192:193], v[12:13], v[110:111], v[192:193]
	v_pk_fma_f32 v[162:163], v[8:9], v[114:115], v[162:163]
	v_pk_fma_f32 v[194:195], v[12:13], v[114:115], v[194:195]
	v_pk_fma_f32 v[164:165], v[8:9], v[118:119], v[164:165]
	v_pk_fma_f32 v[196:197], v[12:13], v[118:119], v[196:197]
	v_pk_fma_f32 v[166:167], v[8:9], v[122:123], v[166:167]
	v_pk_fma_f32 v[198:199], v[12:13], v[122:123], v[198:199]
	v_pk_fma_f32 v[160:161], v[6:7], v[112:113], v[160:161]
	v_pk_fma_f32 v[192:193], v[10:11], v[112:113], v[192:193]
	v_pk_fma_f32 v[162:163], v[6:7], v[116:117], v[162:163]
	v_pk_fma_f32 v[194:195], v[10:11], v[116:117], v[194:195]
	v_pk_fma_f32 v[164:165], v[6:7], v[120:121], v[164:165]
	v_pk_fma_f32 v[196:197], v[10:11], v[120:121], v[196:197]
	v_pk_fma_f32 v[166:167], v[6:7], v[124:125], v[166:167]
	v_pk_fma_f32 v[198:199], v[10:11], v[124:125], v[198:199]
	ds_read_b128 v[228:231], v100 offset:52224
	ds_read_b128 v[232:235], v100 offset:56320
	ds_read_b128 v[236:239], v100 offset:60416
	ds_read_b128 v[240:243], v100 offset:64512
	s_waitcnt lgkmcnt(8)
; #define LAS __attribute__((address_space(3)))
; __device__ __forceinline__ float dot4(const f32x4 a, const f32x4 b) { return (a[0] * b[0] + a[1] * b[1]) + (a[2] * b[2] + a[3] * b[3]); }
; __device__ __forceinline__ float bfly16(const f32x4 p0, const f32x4 p1, const f32x4 p2, const f32x4 p3, int lane) {
;     const bool b3 = lane & 8, b2 = lane & 4, b1 = lane & 2, b0 = lane & 1;
;     const f32x4 s0 = b3 ? p0 : p2, s1 = b3 ? p1 : p3, k0 = b3 ? p2 : p0, k1 = b3 ? p3 : p1;
;     f32x4 a, c;
;     a[0] = k0[0] + __shfl_xor(s0[0], 8); a[1] = k0[1] + __shfl_xor(s0[1], 8); a[2] = k0[2] + __shfl_xor(s0[2], 8); a[3] = k0[3] + __shfl_xor(s0[3], 8);
;     c[0] = k1[0] + __shfl_xor(s1[0], 8); c[1] = k1[1] + __shfl_xor(s1[1], 8); c[2] = k1[2] + __shfl_xor(s1[2], 8); c[3] = k1[3] + __shfl_xor(s1[3], 8);
;     const f32x4 s4 = b2 ? a : c, k4 = b2 ? c : a;
;     const float d0 = k4[0] + __shfl_xor(s4[0], 4), d1 = k4[1] + __shfl_xor(s4[1], 4), d2 = k4[2] + __shfl_xor(s4[2], 4), d3 = k4[3] + __shfl_xor(s4[3], 4);
;     const float e0 = (b1 ? d2 : d0) + __shfl_xor(b1 ? d0 : d2, 2), e1 = (b1 ? d3 : d1) + __shfl_xor(b1 ? d1 : d3, 2);
; __device__ __forceinline__ void norm_rows2(const f32x4 (&xa)[4], const f32x4 (&xb)[4], const LAS float* gsa, const LAS float* sha, const LAS float* gsb, const LAS float* shb, const LAS float* WgT, ...
;     ...
;     f32x4 pa[4], pb[4];
; #pragma unroll
;     for (int jq = 0; jq < 4; ++jq) { f32x4 sa = (f32x4){0.f, 0.f, 0.f, 0.f}, sb = sa;
; #pragma unroll
;         for (int i = 0; i < 4; ++i) { const LAS float* wp = WgT + (jq * 4) * 1024 + i * 256 + lane * 4;
;             const f32x4 w0 = *(const LAS f32x4*)wp, w1 = *(const LAS f32x4*)(wp + 1024), w2 = *(const LAS f32x4*)(wp + 2048), w3 = *(const LAS f32x4*)(wp + 3072);
;             sa += (f32x4){dot4(ya[i], w0), dot4(ya[i], w1), dot4(ya[i], w2), dot4(ya[i], w3)};
;             sb += (f32x4){dot4(yb[i], w0), dot4(yb[i], w1), dot4(yb[i], w2), dot4(yb[i], w3)}; }
;         pa[jq] = sa; pb[jq] = sb; }
	v_pk_fma_f32 v[168:169], v[8:9], v[126:127], v[168:169]
	v_pk_fma_f32 v[200:201], v[12:13], v[126:127], v[200:201]
	v_pk_fma_f32 v[170:171], v[8:9], v[130:131], v[170:171]
	v_pk_fma_f32 v[202:203], v[12:13], v[130:131], v[202:203]
	v_pk_fma_f32 v[172:173], v[8:9], v[134:135], v[172:173]
	v_pk_fma_f32 v[204:205], v[12:13], v[134:135], v[204:205]
	v_pk_fma_f32 v[174:175], v[8:9], v[138:139], v[174:175]
	v_pk_fma_f32 v[206:207], v[12:13], v[138:139], v[206:207]
	v_pk_fma_f32 v[168:169], v[6:7], v[128:129], v[168:169]
	v_pk_fma_f32 v[200:201], v[10:11], v[128:129], v[200:201]
	v_pk_fma_f32 v[170:171], v[6:7], v[132:133], v[170:171]
	v_pk_fma_f32 v[202:203], v[10:11], v[132:133], v[202:203]
	v_pk_fma_f32 v[172:173], v[6:7], v[136:137], v[172:173]
	v_pk_fma_f32 v[204:205], v[10:11], v[136:137], v[204:205]
	v_pk_fma_f32 v[174:175], v[6:7], v[140:141], v[174:175]
	v_pk_fma_f32 v[206:207], v[10:11], v[140:141], v[206:207]
	s_waitcnt lgkmcnt(4)
	v_pk_fma_f32 v[176:177], v[8:9], v[142:143], v[176:177]
	v_pk_fma_f32 v[208:209], v[12:13], v[142:143], v[208:209]
	v_pk_fma_f32 v[178:179], v[8:9], v[146:147], v[178:179]
	v_pk_fma_f32 v[210:211], v[12:13], v[146:147], v[210:211]
	v_pk_fma_f32 v[180:181], v[8:9], v[150:151], v[180:181]
	v_pk_fma_f32 v[212:213], v[12:13], v[150:151], v[212:213]
	v_pk_fma_f32 v[182:183], v[8:9], v[154:155], v[182:183]
	v_pk_fma_f32 v[214:215], v[12:13], v[154:155], v[214:215]
	v_pk_fma_f32 v[176:177], v[6:7], v[144:145], v[176:177]
	v_pk_fma_f32 v[208:209], v[10:11], v[144:145], v[208:209]
	v_pk_fma_f32 v[178:179], v[6:7], v[148:149], v[178:179]
	v_pk_fma_f32 v[210:211], v[10:11], v[148:149], v[210:211]
	v_pk_fma_f32 v[180:181], v[6:7], v[152:153], v[180:181]
	v_pk_fma_f32 v[212:213], v[10:11], v[152:153], v[212:213]
	v_pk_fma_f32 v[182:183], v[6:7], v[156:157], v[182:183]
	v_pk_fma_f32 v[214:215], v[10:11], v[156:157], v[214:215]
	s_waitcnt lgkmcnt(0)
	v_pk_fma_f32 v[184:185], v[8:9], v[228:229], v[184:185]
	v_pk_fma_f32 v[216:217], v[12:13], v[228:229], v[216:217]
	v_pk_fma_f32 v[186:187], v[8:9], v[232:233], v[186:187]
	v_pk_fma_f32 v[218:219], v[12:13], v[232:233], v[218:219]
	v_pk_fma_f32 v[188:189], v[8:9], v[236:237], v[188:189]
	v_pk_fma_f32 v[220:221], v[12:13], v[236:237], v[220:221]
	v_pk_fma_f32 v[190:191], v[8:9], v[240:241], v[190:191]
	v_pk_fma_f32 v[222:223], v[12:13], v[240:241], v[222:223]
	v_pk_fma_f32 v[184:185], v[6:7], v[230:231], v[184:185]
	v_pk_fma_f32 v[216:217], v[10:11], v[230:231], v[216:217]
	v_pk_fma_f32 v[186:187], v[6:7], v[234:235], v[186:187]
	v_pk_fma_f32 v[218:219], v[10:11], v[234:235], v[218:219]
	v_pk_fma_f32 v[188:189], v[6:7], v[238:239], v[188:189]
	v_pk_fma_f32 v[220:221], v[10:11], v[238:239], v[220:221]
	v_pk_fma_f32 v[190:191], v[6:7], v[242:243], v[190:191]
	v_pk_fma_f32 v[222:223], v[10:11], v[242:243], v[222:223]
	v_add_f32_e32 v22, v160, v161
	v_add_f32_e32 v23, v162, v163
	v_add_f32_e32 v24, v164, v165
	v_add_f32_e32 v25, v166, v167
	v_add_f32_e32 v78, v168, v169
	v_add_f32_e32 v79, v170, v171
	v_add_f32_e32 v80, v172, v173
	v_add_f32_e32 v81, v174, v175
	v_add_f32_e32 v86, v176, v177
	v_add_f32_e32 v87, v178, v179
	v_add_f32_e32 v88, v180, v181
	v_add_f32_e32 v89, v182, v183
	v_add_f32_e32 v2, v184, v185
	v_add_f32_e32 v3, v186, v187
	v_add_f32_e32 v0, v188, v189
	v_add_f32_e32 v1, v190, v191
	v_add_f32_e32 v26, v192, v193
	v_add_f32_e32 v27, v194, v195
	v_add_f32_e32 v28, v196, v197
	v_add_f32_e32 v29, v198, v199
	v_add_f32_e32 v82, v200, v201
	v_add_f32_e32 v83, v202, v203
	v_add_f32_e32 v84, v204, v205
	v_add_f32_e32 v85, v206, v207
	v_add_f32_e32 v90, v208, v209
	v_add_f32_e32 v91, v210, v211
	v_add_f32_e32 v92, v212, v213
	v_add_f32_e32 v93, v214, v215
	v_add_f32_e32 v12, v216, v217
	v_add_f32_e32 v13, v218, v219
	v_add_f32_e32 v10, v220, v221
	v_add_f32_e32 v11, v222, v223
	v_cndmask_b32_e64 v21, v85, v11, s[6:7]
	v_cndmask_b32_e64 v20, v84, v10, s[6:7]
	v_add_f32_dpp v110, v22, v22 row_mirror row_mask:0xf bank_mask:0x3
	v_add_f32_dpp v110, v86, v86 row_mirror row_mask:0xf bank_mask:0xc
	v_add_f32_dpp v114, v78, v78 row_mirror row_mask:0xf bank_mask:0x3
	v_add_f32_dpp v114, v2, v2 row_mirror row_mask:0xf bank_mask:0xc
	v_add_f32_dpp v118, v26, v26 row_mirror row_mask:0xf bank_mask:0x3
	v_add_f32_dpp v118, v90, v90 row_mirror row_mask:0xf bank_mask:0xc
	v_add_f32_dpp v122, v82, v82 row_mirror row_mask:0xf bank_mask:0x3
	v_add_f32_dpp v122, v12, v12 row_mirror row_mask:0xf bank_mask:0xc
	v_add_f32_dpp v111, v23, v23 row_mirror row_mask:0xf bank_mask:0x3
	v_add_f32_dpp v111, v87, v87 row_mirror row_mask:0xf bank_mask:0xc
	v_add_f32_dpp v115, v79, v79 row_mirror row_mask:0xf bank_mask:0x3
	v_add_f32_dpp v115, v3, v3 row_mirror row_mask:0xf bank_mask:0xc
	v_add_f32_dpp v119, v27, v27 row_mirror row_mask:0xf bank_mask:0x3
	v_add_f32_dpp v119, v91, v91 row_mirror row_mask:0xf bank_mask:0xc
	v_add_f32_dpp v123, v83, v83 row_mirror row_mask:0xf bank_mask:0x3
	v_add_f32_dpp v123, v13, v13 row_mirror row_mask:0xf bank_mask:0xc
	v_add_f32_dpp v112, v24, v24 row_mirror row_mask:0xf bank_mask:0x3
	v_add_f32_dpp v112, v88, v88 row_mirror row_mask:0xf bank_mask:0xc
	v_add_f32_dpp v116, v80, v80 row_mirror row_mask:0xf bank_mask:0x3
	v_add_f32_dpp v116, v0, v0 row_mirror row_mask:0xf bank_mask:0xc
	v_add_f32_dpp v120, v28, v28 row_mirror row_mask:0xf bank_mask:0x3
	v_add_f32_dpp v120, v92, v92 row_mirror row_mask:0xf bank_mask:0xc
	v_add_f32_dpp v124, v84, v84 row_mirror row_mask:0xf bank_mask:0x3
	v_add_f32_dpp v124, v10, v10 row_mirror row_mask:0xf bank_mask:0xc
	v_add_f32_dpp v113, v25, v25 row_mirror row_mask:0xf bank_mask:0x3
	v_add_f32_dpp v113, v89, v89 row_mirror row_mask:0xf bank_mask:0xc
; __device__ __forceinline__ float log_sigmoid(float x) { return fminf(x, 0.f) - log1pf(expf(-fabsf(x))); }
; __device__ __forceinline__ float bfly16(const f32x4 p0, const f32x4 p1, const f32x4 p2, const f32x4 p3, int lane) {
;     ...
;     const f32x4 s4 = b2 ? a : c, k4 = b2 ? c : a;
;     const float d0 = k4[0] + __shfl_xor(s4[0], 4), d1 = k4[1] + __shfl_xor(s4[1], 4), d2 = k4[2] + __shfl_xor(s4[2], 4), d3 = k4[3] + __shfl_xor(s4[3], 4);
;     const float e0 = (b1 ? d2 : d0) + __shfl_xor(b1 ? d0 : d2, 2), e1 = (b1 ? d3 : d1) + __shfl_xor(b1 ? d1 : d3, 2);
;     float q1 = (b0 ? e1 : e0) + __shfl_xor(b0 ? e0 : e1, 1);
;     q1 += __shfl_xor(q1, 16); q1 += __shfl_xor(q1, 32);
;     return q1;
; __device__ __forceinline__ void norm_rows2(const f32x4 (&xa)[4], const f32x4 (&xb)[4], const LAS float* gsa, const LAS float* sha, const LAS float* gsb, const LAS float* shb, const LAS float* WgT, ...
;     ...
;     if (lane < 16) { const float gbv = gate_b[lane]; const bool ls = (lane >> 2) & 1;
;         const float prea = qa + gbv, preb = qb + gbv;
;         ga[0] = ls ? log_sigmoid(prea) : prea; gb[0] = ls ? log_sigmoid(preb) : preb; }
	v_add_f32_dpp v117, v81, v81 row_mirror row_mask:0xf bank_mask:0x3
	v_add_f32_dpp v117, v1, v1 row_mirror row_mask:0xf bank_mask:0xc
	v_add_f32_dpp v121, v29, v29 row_mirror row_mask:0xf bank_mask:0x3
	v_add_f32_dpp v121, v93, v93 row_mirror row_mask:0xf bank_mask:0xc
	v_add_f32_dpp v125, v85, v85 row_mirror row_mask:0xf bank_mask:0x3
	v_add_f32_dpp v125, v11, v11 row_mirror row_mask:0xf bank_mask:0xc
	v_add_f32_dpp v126, v110, v110 row_half_mirror row_mask:0xf bank_mask:0x5
	v_add_f32_dpp v126, v114, v114 row_half_mirror row_mask:0xf bank_mask:0xa
	v_add_f32_dpp v130, v118, v118 row_half_mirror row_mask:0xf bank_mask:0x5
	v_add_f32_dpp v130, v122, v122 row_half_mirror row_mask:0xf bank_mask:0xa
	v_add_f32_dpp v127, v111, v111 row_half_mirror row_mask:0xf bank_mask:0x5
	v_add_f32_dpp v127, v115, v115 row_half_mirror row_mask:0xf bank_mask:0xa
	v_add_f32_dpp v131, v119, v119 row_half_mirror row_mask:0xf bank_mask:0x5
	v_add_f32_dpp v131, v123, v123 row_half_mirror row_mask:0xf bank_mask:0xa
	v_add_f32_dpp v128, v112, v112 row_half_mirror row_mask:0xf bank_mask:0x5
	v_add_f32_dpp v128, v116, v116 row_half_mirror row_mask:0xf bank_mask:0xa
	v_add_f32_dpp v132, v120, v120 row_half_mirror row_mask:0xf bank_mask:0x5
	v_add_f32_dpp v132, v124, v124 row_half_mirror row_mask:0xf bank_mask:0xa
	v_add_f32_dpp v129, v113, v113 row_half_mirror row_mask:0xf bank_mask:0x5
	v_add_f32_dpp v129, v117, v117 row_half_mirror row_mask:0xf bank_mask:0xa
	v_add_f32_dpp v133, v121, v121 row_half_mirror row_mask:0xf bank_mask:0x5
	v_add_f32_dpp v133, v125, v125 row_half_mirror row_mask:0xf bank_mask:0xa
	v_cndmask_b32_e64 v134, v128, v126, s[12:13]
	v_cndmask_b32_e64 v135, v126, v128, s[12:13]
	v_cndmask_b32_e64 v136, v129, v127, s[12:13]
	v_cndmask_b32_e64 v137, v127, v129, s[12:13]
	v_cndmask_b32_e64 v138, v132, v130, s[12:13]
	v_cndmask_b32_e64 v139, v130, v132, s[12:13]
	v_cndmask_b32_e64 v140, v133, v131, s[12:13]
	v_cndmask_b32_e64 v141, v131, v133, s[12:13]
	v_add_f32_dpp v134, v135, v134 quad_perm:[2,3,0,1] row_mask:0xf bank_mask:0xf
	v_add_f32_dpp v136, v137, v136 quad_perm:[2,3,0,1] row_mask:0xf bank_mask:0xf
	v_add_f32_dpp v138, v139, v138 quad_perm:[2,3,0,1] row_mask:0xf bank_mask:0xf
	v_add_f32_dpp v140, v141, v140 quad_perm:[2,3,0,1] row_mask:0xf bank_mask:0xf
	v_cndmask_b32_e64 v143, v134, v136, s[14:15]
	v_cndmask_b32_e64 v127, v138, v140, s[14:15]
	v_cndmask_b32_e64 v142, v136, v134, s[14:15]
	v_cndmask_b32_e64 v126, v140, v138, s[14:15]
	v_add_f32_dpp v1, v143, v142 quad_perm:[1,0,3,2] row_mask:0xf bank_mask:0xf
	v_add_f32_dpp v0, v127, v126 quad_perm:[1,0,3,2] row_mask:0xf bank_mask:0xf
	ds_bpermute_b32 v2, v94, v0
	ds_bpermute_b32 v3, v94, v1
	s_waitcnt lgkmcnt(0)
	v_pk_add_f32 v[0:1], v[0:1], v[2:3]
	ds_bpermute_b32 v2, v53, v0
	ds_bpermute_b32 v3, v53, v1
	s_and_saveexec_b64 s[30:31], s[16:17]
	s_cbranch_execz .LBB0_109
	global_load_dword v4, v[44:45], off
	s_waitcnt lgkmcnt(0)
	v_pk_add_f32 v[0:1], v[0:1], v[2:3]
	s_waitcnt vmcnt(0)
	v_pk_add_f32 v[0:1], v[0:1], v[4:5] op_sel_hi:[1,0]
	s_and_saveexec_b64 s[80:81], s[10:11]
	s_cbranch_execz .LBB0_108
	v_mul_f32_e64 v2, |v0|, s35
	v_rndne_f32_e32 v3, v2
	v_sub_f32_e32 v4, v2, v3
	v_fma_f32 v2, |v0|, s35, -v2
	v_fma_f32 v2, |v0|, s47, v2
	v_add_f32_e32 v2, v4, v2
	v_exp_f32_e32 v4, v2
	v_cvt_i32_f32_e32 v3, v3
	v_cmp_ngt_f32_e64 s[28:29], |v0|, s53
	v_max_f32_e32 v2, v0, v0
	v_min_f32_e32 v2, 0, v2
	v_ldexp_f32 v3, v4, v3
	v_cndmask_b32_e64 v3, 0, v3, s[28:29]
	v_cmp_nlt_f32_e64 s[28:29], |v0|, s75
	s_nop 1
	v_cndmask_b32_e64 v30, v107, v3, s[28:29]
	v_add_f32_e32 v6, 1.0, v30
	v_add_f32_e32 v0, -1.0, v6
	v_sub_f32_e32 v3, v0, v6
	v_add_f32_e32 v3, 1.0, v3
	v_sub_f32_e32 v0, v30, v0
	v_add_f32_e32 v7, v0, v3
	v_mul_f32_e64 v0, |v1|, s35
	v_rndne_f32_e32 v3, v0
	v_sub_f32_e32 v9, v0, v3
	v_fma_f32 v0, |v1|, s35, -v0
	v_fma_f32 v0, |v1|, s47, v0
	v_add_f32_e32 v0, v9, v0
	v_exp_f32_e32 v0, v0
	v_cvt_i32_f32_e32 v9, v3
	v_cmp_ngt_f32_e64 s[28:29], |v1|, s53
	v_cvt_f64_f32_e32 v[4:5], v6
	v_frexp_exp_i32_f64_e32 v4, v[4:5]
	v_ldexp_f32 v0, v0, v9
	v_cndmask_b32_e64 v0, 0, v0, s[28:29]
	v_cmp_nlt_f32_e64 s[28:29], |v1|, s75
	v_max_f32_e32 v3, v1, v1
	v_frexp_mant_f32_e32 v8, v6
	v_cndmask_b32_e64 v31, v107, v0, s[28:29]
	v_add_f32_e32 v5, 1.0, v31
	v_add_f32_e32 v0, -1.0, v5
	v_sub_f32_e32 v1, v0, v5
	v_add_f32_e32 v1, 1.0, v1
	v_sub_f32_e32 v0, v31, v0
	v_add_f32_e32 v9, v0, v1
	v_frexp_mant_f32_e32 v10, v5
	v_cvt_f64_f32_e32 v[0:1], v5
	v_frexp_exp_i32_f64_e32 v0, v[0:1]
	v_cmp_gt_f32_e64 s[28:29], s79, v10
	v_min_f32_e32 v3, 0, v3
	s_nop 0
	v_subbrev_co_u32_e64 v22, s[28:29], 0, v0, s[28:29]
	v_cmp_gt_f32_e64 s[28:29], s79, v8
	s_nop 1
	v_subbrev_co_u32_e64 v23, s[28:29], 0, v4, s[28:29]
	v_sub_u32_e32 v1, 0, v23
	v_ldexp_f32 v0, v6, v1
	v_sub_u32_e32 v6, 0, v22
	v_ldexp_f32 v4, v7, v1
	v_ldexp_f32 v1, v5, v6
	v_ldexp_f32 v5, v9, v6
	v_pk_add_f32 v[6:7], v[0:1], 1.0 op_sel_hi:[1,0]
	v_pk_add_f32 v[14:15], v[0:1], -1.0 op_sel_hi:[1,0]
	v_pk_add_f32 v[8:9], v[6:7], -1.0 op_sel_hi:[1,0]
	v_pk_add_f32 v[16:17], v[14:15], 1.0 op_sel_hi:[1,0]
	v_pk_add_f32 v[8:9], v[0:1], v[8:9] neg_lo:[0,1] neg_hi:[0,1]
	v_pk_add_f32 v[0:1], v[0:1], v[16:17] neg_lo:[0,1] neg_hi:[0,1]
	v_pk_add_f32 v[8:9], v[4:5], v[8:9]
	v_pk_add_f32 v[0:1], v[4:5], v[0:1]
	v_pk_add_f32 v[10:11], v[6:7], v[8:9]
	v_pk_add_f32 v[4:5], v[14:15], v[0:1]
	v_rcp_f32_e32 v12, v10
	v_rcp_f32_e32 v13, v11
	v_pk_add_f32 v[6:7], v[6:7], v[10:11] neg_lo:[0,1] neg_hi:[0,1]
	v_pk_add_f32 v[14:15], v[14:15], v[4:5] neg_lo:[0,1] neg_hi:[0,1]
	v_pk_add_f32 v[6:7], v[8:9], v[6:7]
	v_pk_mul_f32 v[8:9], v[4:5], v[12:13]
	v_pk_add_f32 v[0:1], v[0:1], v[14:15]
; __device__ __forceinline__ float log_sigmoid(float x) { return fminf(x, 0.f) - log1pf(expf(-fabsf(x))); }
; __device__ __forceinline__ void norm_rows2(const f32x4 (&xa)[4], const f32x4 (&xb)[4], const LAS float* gsa, const LAS float* sha, const LAS float* gsb, const LAS float* shb, const LAS float* WgT, ...
;     ...
;     if (lane < 16) { const float gbv = gate_b[lane]; const bool ls = (lane >> 2) & 1;
;         const float prea = qa + gbv, preb = qb + gbv;
;         ga[0] = ls ? log_sigmoid(prea) : prea; gb[0] = ls ? log_sigmoid(preb) : preb; }
	v_pk_mul_f32 v[14:15], v[10:11], v[8:9]
	v_cmp_neq_f32_e64 s[28:29], s77, v30
	v_pk_fma_f32 v[16:17], v[8:9], v[10:11], v[14:15] neg_lo:[0,0,1] neg_hi:[0,0,1]
	s_nop 0
	v_pk_fma_f32 v[16:17], v[8:9], v[6:7], v[16:17]
	s_nop 0
	v_pk_add_f32 v[18:19], v[14:15], v[16:17]
	s_nop 0
	v_pk_add_f32 v[20:21], v[4:5], v[18:19] neg_lo:[0,1] neg_hi:[0,1]
	v_pk_add_f32 v[14:15], v[18:19], v[14:15] neg_lo:[0,1] neg_hi:[0,1]
	v_pk_add_f32 v[4:5], v[4:5], v[20:21] neg_lo:[0,1] neg_hi:[0,1]
	s_nop 0
	v_pk_add_f32 v[4:5], v[4:5], v[18:19] neg_lo:[0,1] neg_hi:[0,1]
	s_nop 0
	v_pk_add_f32 v[0:1], v[0:1], v[4:5]
	v_pk_add_f32 v[4:5], v[14:15], v[16:17] neg_lo:[0,1] neg_hi:[0,1]
	s_nop 0
	v_pk_add_f32 v[0:1], v[4:5], v[0:1]
	s_nop 0
	v_pk_add_f32 v[4:5], v[20:21], v[0:1]
	s_nop 0
	v_pk_mul_f32 v[14:15], v[12:13], v[4:5]
	s_nop 0
	v_pk_mul_f32 v[16:17], v[10:11], v[14:15]
	s_nop 0
	v_pk_fma_f32 v[10:11], v[14:15], v[10:11], v[16:17] neg_lo:[0,0,1] neg_hi:[0,0,1]
	s_nop 0
	v_pk_fma_f32 v[6:7], v[14:15], v[6:7], v[10:11]
	v_pk_add_f32 v[10:11], v[20:21], v[4:5] neg_lo:[0,1] neg_hi:[0,1]
	s_nop 0
	v_pk_add_f32 v[0:1], v[0:1], v[10:11]
	v_pk_add_f32 v[10:11], v[16:17], v[6:7]
	s_nop 0
	v_pk_add_f32 v[18:19], v[4:5], v[10:11] neg_lo:[0,1] neg_hi:[0,1]
	v_pk_add_f32 v[16:17], v[10:11], v[16:17] neg_lo:[0,1] neg_hi:[0,1]
	v_pk_add_f32 v[4:5], v[4:5], v[18:19] neg_lo:[0,1] neg_hi:[0,1]
	s_nop 0
	v_pk_add_f32 v[4:5], v[4:5], v[10:11] neg_lo:[0,1] neg_hi:[0,1]
	s_nop 0
	v_pk_add_f32 v[0:1], v[0:1], v[4:5]
	v_pk_add_f32 v[4:5], v[16:17], v[6:7] neg_lo:[0,1] neg_hi:[0,1]
	s_nop 0
	v_pk_add_f32 v[0:1], v[4:5], v[0:1]
	v_pk_add_f32 v[4:5], v[8:9], v[14:15]
	v_pk_add_f32 v[0:1], v[18:19], v[0:1]
	v_pk_add_f32 v[6:7], v[4:5], v[8:9] neg_lo:[0,1] neg_hi:[0,1]
	v_pk_mul_f32 v[0:1], v[12:13], v[0:1]
	v_pk_add_f32 v[6:7], v[14:15], v[6:7] neg_lo:[0,1] neg_hi:[0,1]
	v_cvt_f32_i32_e32 v9, v22
	v_pk_add_f32 v[0:1], v[6:7], v[0:1]
	v_cvt_f32_i32_e32 v8, v23
	v_pk_add_f32 v[6:7], v[4:5], v[0:1]
	v_pk_mul_f32 v[14:15], v[8:9], s[76:77] op_sel_hi:[1,0]
	v_pk_mul_f32 v[10:11], v[6:7], v[6:7]
	v_pk_add_f32 v[4:5], v[6:7], v[4:5] neg_lo:[0,1] neg_hi:[0,1]
	v_pk_fma_f32 v[12:13], v[10:11], s[52:53], v[52:53] op_sel_hi:[1,0,0]
	v_pk_add_f32 v[0:1], v[0:1], v[4:5] neg_lo:[0,1] neg_hi:[0,1]
	v_ldexp_f32 v4, v6, 1
	v_pk_fma_f32 v[12:13], v[10:11], v[12:13], s[74:75] op_sel_hi:[1,1,0]
	v_ldexp_f32 v5, v7, 1
	v_pk_mul_f32 v[6:7], v[6:7], v[10:11]
	v_pk_fma_f32 v[16:17], v[8:9], s[76:77], v[14:15] op_sel_hi:[1,0,1] neg_lo:[0,0,1] neg_hi:[0,0,1]
	v_pk_mul_f32 v[6:7], v[6:7], v[12:13]
	v_mov_b32_e32 v19, v5
	v_pk_add_f32 v[10:11], v[4:5], v[6:7]
	v_ldexp_f32 v0, v0, 1
	v_pk_add_f32 v[4:5], v[10:11], v[4:5] neg_lo:[0,1] neg_hi:[0,1]
	v_pk_fma_f32 v[8:9], v[8:9], s[78:79], v[16:17] op_sel_hi:[1,0,1]
	v_ldexp_f32 v1, v1, 1
	v_pk_add_f32 v[4:5], v[6:7], v[4:5] neg_lo:[0,1] neg_hi:[0,1]
	v_mov_b32_e32 v12, v14
	v_mov_b32_e32 v13, v7
	v_mov_b32_e32 v18, v8
	v_pk_add_f32 v[6:7], v[0:1], v[4:5]
	v_mov_b32_e32 v4, v14
	v_mov_b32_e32 v0, v8
	v_pk_add_f32 v[12:13], v[12:13], v[18:19]
	v_pk_add_f32 v[18:19], v[4:5], v[0:1]
	v_mov_b32_e32 v0, v10
	v_mov_b32_e32 v4, v6
	v_pk_add_f32 v[16:17], v[14:15], v[8:9]
	v_pk_add_f32 v[0:1], v[0:1], v[4:5]
	v_pk_add_f32 v[4:5], v[10:11], v[6:7]
	v_mov_b32_e32 v20, v16
	v_mov_b32_e32 v21, v15
	v_mov_b32_e32 v22, v4
	v_mov_b32_e32 v23, v9
	v_pk_add_f32 v[0:1], v[12:13], v[0:1]
	v_pk_add_f32 v[12:13], v[16:17], v[4:5]
	v_pk_add_f32 v[24:25], v[20:21], v[22:23]
	v_mov_b32_e32 v26, v4
	v_mov_b32_e32 v27, v13
	v_mov_b32_e32 v28, v10
	v_mov_b32_e32 v29, v17
	v_pk_add_f32 v[20:21], v[24:25], v[20:21] neg_lo:[0,1] neg_hi:[0,1]
	v_pk_add_f32 v[26:27], v[26:27], v[28:29] neg_lo:[0,1] neg_hi:[0,1]
	v_pk_add_f32 v[24:25], v[16:17], v[14:15] neg_lo:[0,1] neg_hi:[0,1]
	v_pk_add_f32 v[22:23], v[22:23], v[20:21] neg_lo:[0,1] neg_hi:[0,1]
	v_mov_b32_e32 v28, v16
	v_mov_b32_e32 v29, v13
	v_mov_b32_e32 v15, v27
	v_mov_b32_e32 v21, v11
	v_pk_add_f32 v[10:11], v[4:5], v[10:11] neg_lo:[0,1] neg_hi:[0,1]
	v_pk_add_f32 v[14:15], v[28:29], v[14:15] neg_lo:[0,1] neg_hi:[0,1]
	v_pk_add_f32 v[24:25], v[8:9], v[24:25] neg_lo:[0,1] neg_hi:[0,1]
	v_pk_add_f32 v[0:1], v[0:1], v[20:21] neg_lo:[0,1] neg_hi:[0,1]
	v_pk_add_f32 v[10:11], v[6:7], v[10:11] neg_lo:[0,1] neg_hi:[0,1]
	v_mov_b32_e32 v9, v17
	v_mov_b32_e32 v7, v5
	v_pk_add_f32 v[0:1], v[18:19], v[0:1] neg_lo:[0,1] neg_hi:[0,1]
	v_pk_add_f32 v[8:9], v[8:9], v[14:15] neg_lo:[0,1] neg_hi:[0,1]
	v_pk_add_f32 v[4:5], v[6:7], v[26:27] neg_lo:[0,1] neg_hi:[0,1]
	v_pk_add_f32 v[14:15], v[22:23], v[0:1]
	v_pk_add_f32 v[6:7], v[4:5], v[8:9]
	v_mov_b32_e32 v5, v1
	v_pk_add_f32 v[0:1], v[24:25], v[4:5]
	v_mov_b32_e32 v9, v23
	v_pk_add_f32 v[0:1], v[0:1], v[8:9] neg_lo:[0,1] neg_hi:[0,1]
	v_mov_b32_e32 v4, v6
	v_mov_b32_e32 v5, v15
	v_pk_add_f32 v[4:5], v[4:5], v[0:1] neg_lo:[0,1] neg_hi:[0,1]
	v_pk_add_f32 v[0:1], v[10:11], v[0:1] neg_lo:[0,1] neg_hi:[0,1]
	v_pk_add_f32 v[4:5], v[8:9], v[4:5] neg_lo:[0,1] neg_hi:[0,1]
	s_nop 0
	v_pk_add_f32 v[0:1], v[0:1], v[4:5]
	v_pk_add_f32 v[4:5], v[14:15], v[6:7]
	s_nop 0
	v_pk_add_f32 v[6:7], v[12:13], v[4:5]
	s_nop 0
	v_pk_add_f32 v[8:9], v[6:7], v[12:13] neg_lo:[0,1] neg_hi:[0,1]
	s_nop 0
	v_pk_add_f32 v[4:5], v[4:5], v[8:9] neg_lo:[0,1] neg_hi:[0,1]
	s_nop 0
	v_pk_add_f32 v[0:1], v[0:1], v[4:5]
	s_nop 0
	v_pk_add_f32 v[0:1], v[6:7], v[0:1]
	s_nop 0
	v_cndmask_b32_e64 v0, v107, v0, s[28:29]
	v_cmp_neq_f32_e64 s[28:29], s77, v31
	s_nop 1
	v_cndmask_b32_e64 v1, v107, v1, s[28:29]
	v_cmp_lt_f32_e64 s[28:29], |v31|, s92
	s_nop 1
	v_cndmask_b32_e64 v1, v1, v31, s[28:29]
	v_cmp_lt_f32_e64 s[28:29], |v30|, s92
	s_nop 1
	v_cndmask_b32_e64 v0, v0, v30, s[28:29]
	v_pk_add_f32 v[0:1], v[2:3], v[0:1] neg_lo:[0,1] neg_hi:[0,1]
	s_branch .LBB0_108
